# SWA phase: next-unit q prefetch into spare VGPRs, stale vmcnt waits removed, sample K/V cache prefetch de-serialized, conv second items moved to short-attention workgroups
# speedup vs baseline: 1.0108x; 1.0067x over previous
.LBB0_410:
	s_or_b64 exec, exec, s[10:11]
	s_cmpk_eq_i32 s34, 0x100
	s_cbranch_scc1 .Lconv_rebal
	s_add_i32 s3, s3, s34
	s_cmpk_lt_i32 s3, 0x110
	v_add_u32_e32 v80, s95, v80
	s_cbranch_scc0 .LBB0_404
	s_branch .LBB0_411
.Lconv_rebal:
	s_cmpk_gt_i32 s3, 0xff
	s_cbranch_scc1 .LBB0_404
	s_and_b32 s100, s2, 0x78
	s_cmp_lg_u32 s100, 0
	s_cbranch_scc1 .LBB0_404
	s_lshr_b32 s100, s2, 7
	s_lshl_b32 s100, s100, 3
	s_and_b32 s10, s2, 7
	s_add_i32 s100, s100, s10
	s_addk_i32 s100, 0x100
	s_sub_i32 s10, s100, s3
	s_lshl_b32 s10, s10, 6
	v_add_u32_e32 v80, s10, v80
	s_mov_b32 s3, s100

.LBB0_430:
	s_mov_b32 s101, 0
	v_mov_b32_e32 v104, 0
	s_mov_b32 s88, s2
	v_readlane_b32 s16, v254, 53
	v_readlane_b32 s20, v254, 22
	v_mov_b32_e32 v105, v104
	v_mov_b32_e32 v106, v104
	v_mov_b32_e32 v107, v104
	v_mov_b32_e32 v108, v104
	v_mov_b32_e32 v109, v104
	v_mov_b32_e32 v110, v104
	v_mov_b32_e32 v111, v104
	v_mov_b32_e32 v112, v104
	v_mov_b32_e32 v113, v104
	v_mov_b32_e32 v114, v104
	v_mov_b32_e32 v115, v104
	s_waitcnt vmcnt(4)
	v_mov_b32_e32 v116, v104
	v_mov_b32_e32 v117, v104
	v_mov_b32_e32 v118, v104
	v_mov_b32_e32 v119, v104
	s_branch .LBB0_433

.LBB0_439:
	s_or_b64 exec, exec, s[0:1]
	v_lshrrev_b32_e32 v0, 1, v65
	v_and_b32_e32 v3, 32, v0
	v_and_b32_e32 v66, 31, v65
	v_or_b32_e32 v67, v3, v66
	v_ashrrev_i32_e32 v2, 7, v65
	v_add_u32_e32 v4, v67, v1
	v_lshl_add_u32 v2, s20, 2, v2
	v_ashrrev_i32_e32 v5, 31, v4
	v_lshlrev_b64 v[4:5], 11, v[4:5]
	v_lshlrev_b32_e32 v6, 6, v2
	v_lshl_add_u64 v[4:5], s[44:45], 0, v[4:5]
	v_ashrrev_i32_e32 v7, 31, v6
	v_cmp_gt_i32_e64 s[0:1], s16, v3
	v_lshl_add_u64 v[154:155], v[6:7], 1, v[4:5]
	s_and_saveexec_b64 s[10:11], s[0:1]
	s_cbranch_execz .LBB0_441
	s_cmp_lg_u32 s101, 0
	s_cbranch_scc1 .Lswa_qhave
	v_and_b32_e32 v194, 16, v0
	v_lshl_add_u64 v[0:1], v[154:155], 0, v[194:195]
	global_load_dwordx4 v[136:139], v[0:1], off
	global_load_dwordx4 v[140:143], v[0:1], off offset:32
	global_load_dwordx4 v[144:147], v[0:1], off offset:64
	global_load_dwordx4 v[148:151], v[0:1], off offset:96
	s_waitcnt vmcnt(0)
.Lswa_qhave:
	v_mov_b32_e32 v104, v136
	v_mov_b32_e32 v105, v137
	v_mov_b32_e32 v106, v138
	v_mov_b32_e32 v107, v139
	v_mov_b32_e32 v108, v140
	v_mov_b32_e32 v109, v141
	v_mov_b32_e32 v110, v142
	v_mov_b32_e32 v111, v143
	v_mov_b32_e32 v112, v144
	v_mov_b32_e32 v113, v145
	v_mov_b32_e32 v114, v146
	v_mov_b32_e32 v115, v147
	v_mov_b32_e32 v116, v148
	v_mov_b32_e32 v117, v149
	v_mov_b32_e32 v118, v150
	v_mov_b32_e32 v119, v151

.LBB0_446:
	v_lshlrev_b32_e32 v0, 3, v4
	s_lshl_b32 s33, s89, 3
	s_and_b32 s54, s88, 3
	v_lshrrev_b32_e32 v134, 1, v121
	v_and_b32_e32 v135, 32, v134
	v_cmp_gt_i32_e64 s[28:29], s51, v135
	v_and_b32_e32 v152, 31, v121
	v_or_b32_e32 v152, v135, v152
	v_add_u32_e32 v152, s50, v152
	v_ashrrev_i32_e32 v153, 31, v152
	v_lshlrev_b64 v[152:153], 11, v[152:153]
	v_lshl_add_u64 v[152:153], s[44:45], 0, v[152:153]
	v_ashrrev_i32_e32 v135, 7, v121
	v_lshl_add_u32 v135, s54, 2, v135
	v_lshlrev_b32_e32 v135, 7, v135
	v_and_b32_e32 v134, 16, v134
	v_add_u32_e32 v134, v135, v134
	v_mov_b32_e32 v135, 0
	v_lshl_add_u64 v[152:153], v[152:153], 0, v[134:135]
	s_and_saveexec_b64 s[28:29], s[28:29]
	global_load_dwordx4 v[136:139], v[152:153], off
	global_load_dwordx4 v[140:143], v[152:153], off offset:32
	global_load_dwordx4 v[144:147], v[152:153], off offset:64
	global_load_dwordx4 v[148:151], v[152:153], off offset:96
	s_or_b64 exec, exec, s[28:29]
	s_mov_b32 s101, 1
	v_and_b32_e32 v3, 56, v0
	v_cmp_gt_i32_e32 vcc, s33, v4
	s_and_saveexec_b64 s[24:25], vcc
	s_cbranch_execz .LBB0_452
	v_ashrrev_i32_e32 v0, 3, v4
	v_cmp_lt_i32_e32 vcc, s83, v0
	s_xor_b64 s[28:29], s[22:23], -1
	s_or_b64 s[28:29], s[28:29], vcc
	s_lshl_b32 s92, s54, 6
	s_and_saveexec_b64 s[42:43], s[28:29]
	s_xor_b64 s[28:29], exec, s[42:43]
	s_cbranch_execz .LBB0_449
	v_add_u32_e32 v0, s26, v0
	v_ashrrev_i32_e32 v1, 31, v0
	v_readlane_b32 s42, v254, 23
	v_lshlrev_b64 v[0:1], 10, v[0:1]
	v_readlane_b32 s43, v254, 24
	v_lshlrev_b32_e32 v194, 1, v3
	s_nop 0
	v_lshl_add_u64 v[0:1], s[42:43], 0, v[0:1]
	s_lshl_b32 s42, s92, 1
	s_mov_b32 s43, s93
	v_lshl_add_u64 v[0:1], v[0:1], 0, s[42:43]
	v_lshl_add_u64 v[0:1], v[0:1], 0, v[194:195]
	global_load_dwordx4 v[80:83], v[0:1], off
	global_load_dwordx4 v[92:95], v[0:1], off offset:512
.LBB0_449:
	s_andn2_saveexec_b64 s[28:29], s[28:29]
	s_cbranch_execz .LBB0_451
	v_ashrrev_i32_e32 v1, 31, v0
	v_lshlrev_b64 v[0:1], 8, v[0:1]
	s_or_b64 s[72:73], s[92:93], s[14:15]
	s_ashr_i32 s11, s10, 31
	v_lshl_add_u64 v[0:1], s[72:73], 0, v[0:1]
	s_lshl_b64 s[42:43], s[10:11], 15
	v_or_b32_e32 v0, v0, v3
	v_lshl_add_u64 v[0:1], v[0:1], 0, s[42:43]
	v_readlane_b32 s56, v253, 42
	v_lshlrev_b64 v[0:1], 2, v[0:1]
	v_readlane_b32 s62, v253, 48
	v_readlane_b32 s63, v253, 49
	v_readlane_b32 s64, v253, 50
	v_readlane_b32 s65, v253, 51
	v_lshl_add_u64 v[10:11], s[62:63], 0, v[0:1]
	global_load_dwordx4 v[6:9], v[10:11], off offset:16
	s_nop 0
	global_load_dwordx4 v[10:13], v[10:11], off
	v_lshl_add_u64 v[0:1], s[64:65], 0, v[0:1]
	global_load_dwordx4 v[14:17], v[0:1], off offset:16
	global_load_dwordx4 v[18:21], v[0:1], off
	v_readlane_b32 s57, v253, 43
	v_readlane_b32 s58, v253, 44
	v_readlane_b32 s59, v253, 45
	v_readlane_b32 s60, v253, 46
	v_readlane_b32 s61, v253, 47
	v_readlane_b32 s66, v253, 52
	v_readlane_b32 s67, v253, 53
	v_readlane_b32 s68, v253, 54
	v_readlane_b32 s69, v253, 55
	v_readlane_b32 s70, v253, 56
	v_readlane_b32 s71, v253, 57
	s_waitcnt vmcnt(3)
	v_cvt_pk_bf16_f32 v82, v6, v7
	s_waitcnt vmcnt(2)
	v_cvt_pk_bf16_f32 v80, v10, v11
	v_cvt_pk_bf16_f32 v81, v12, v13
	v_cvt_pk_bf16_f32 v83, v8, v9
	s_waitcnt vmcnt(1)
	v_cvt_pk_bf16_f32 v94, v14, v15
	s_waitcnt vmcnt(0)
	v_cvt_pk_bf16_f32 v92, v18, v19
	v_cvt_pk_bf16_f32 v93, v20, v21
	v_cvt_pk_bf16_f32 v95, v16, v17

.LBB0_455:
	s_andn2_saveexec_b64 s[28:29], s[28:29]
	s_cbranch_execz .LBB0_457
	v_ashrrev_i32_e32 v1, 31, v0
	v_mov_b32_e32 v5, s35
	s_ashr_i32 s11, s10, 31
	v_lshlrev_b64 v[0:1], 8, v[0:1]
	v_or3_b32 v202, s14, v5, v3
	s_lshl_b64 s[42:43], s[10:11], 15
	v_lshl_add_u64 v[0:1], v[202:203], 0, v[0:1]
	v_lshl_add_u64 v[0:1], v[0:1], 0, s[42:43]
	v_readlane_b32 s56, v253, 42
	v_lshlrev_b64 v[0:1], 2, v[0:1]
	v_readlane_b32 s62, v253, 48
	v_readlane_b32 s63, v253, 49
	v_readlane_b32 s64, v253, 50
	v_readlane_b32 s65, v253, 51
	v_lshl_add_u64 v[10:11], s[62:63], 0, v[0:1]
	global_load_dwordx4 v[6:9], v[10:11], off offset:16
	s_nop 0
	global_load_dwordx4 v[10:13], v[10:11], off
	v_lshl_add_u64 v[0:1], s[64:65], 0, v[0:1]
	global_load_dwordx4 v[14:17], v[0:1], off offset:16
	global_load_dwordx4 v[18:21], v[0:1], off
	v_readlane_b32 s57, v253, 43
	v_readlane_b32 s58, v253, 44
	v_readlane_b32 s59, v253, 45
	v_readlane_b32 s60, v253, 46
	v_readlane_b32 s61, v253, 47
	v_readlane_b32 s66, v253, 52
	v_readlane_b32 s67, v253, 53
	v_readlane_b32 s68, v253, 54
	v_readlane_b32 s69, v253, 55
	v_readlane_b32 s70, v253, 56
	v_readlane_b32 s71, v253, 57
	s_waitcnt vmcnt(3)
	v_cvt_pk_bf16_f32 v90, v6, v7
	s_waitcnt vmcnt(2)
	v_cvt_pk_bf16_f32 v88, v10, v11
	v_cvt_pk_bf16_f32 v89, v12, v13
	v_cvt_pk_bf16_f32 v91, v8, v9
	s_waitcnt vmcnt(1)
	v_cvt_pk_bf16_f32 v98, v14, v15
	s_waitcnt vmcnt(0)
	v_cvt_pk_bf16_f32 v96, v18, v19
	v_cvt_pk_bf16_f32 v97, v20, v21
	v_cvt_pk_bf16_f32 v99, v16, v17

.LBB0_469:
	v_mov_b32_e32 v0, v161
	s_branch .LBB0_472
.LBB0_470:
	s_mov_b64 s[0:1], 0
	v_mov_b32_e32 v0, v161
	s_cbranch_execz .LBB0_472
	s_cmp_lg_u32 s20, 0
	s_cselect_b64 s[0:1], -1, 0
	v_mov_b32_e32 v0, v160
.LBB0_472:
	s_andn2_b64 vcc, exec, s[0:1]
	s_cbranch_vccnz .LBB0_474
	s_cmp_eq_u32 s20, 2
	s_cselect_b64 vcc, -1, 0
	s_nop 1
	v_cndmask_b32_e32 v0, v163, v162, vcc
.LBB0_474:
	v_add_u32_e32 v1, 1, v2
	v_cvt_f32_i32_e32 v1, v1
	s_mov_b32 s0, 0xc2fc0000
	v_and_b32_e32 v68, 63, v65
	v_lshrrev_b32_e32 v70, 5, v68
	v_mul_f32_e32 v2, -0.5, v1
	v_cmp_gt_f32_e32 vcc, s0, v2
	v_mul_f32_e32 v164, 0x3fb8aa3b, v0
	s_cmpk_lg_i32 s3, 0xc0
	v_cndmask_b32_e32 v2, 0, v244, vcc
	v_fmac_f32_e32 v2, -0.5, v1
	v_exp_f32_e32 v1, v2
	v_cndmask_b32_e32 v2, 0, v245, vcc
	s_mov_b64 s[0:1], -1
	v_lshlrev_b32_e32 v69, 4, v70
	v_ldexp_f32 v1, v1, v2
	v_mul_f32_e32 v157, 0x3fb8aa3b, v1
	s_cbranch_scc0 .LBB0_500
	v_mad_u32_u24 v0, v66, s17, 0
	v_add_u32_e32 v72, v0, v69
	ds_read_b128 v[0:3], v72
	ds_read_b128 v[4:7], v72 offset:32
	s_cmpk_gt_u32 s3, 0x5f
	s_cselect_b64 s[10:11], -1, 0
	s_cmpk_lt_u32 s3, 0x60
	s_waitcnt lgkmcnt(1)
	v_mfma_f32_32x32x16_bf16 v[16:31], v[0:3], v[104:107], 0
	ds_read_b128 v[0:3], v72 offset:64
	ds_read_b128 v[32:35], v72 offset:4640
	s_waitcnt lgkmcnt(2)
	v_mfma_f32_32x32x16_bf16 v[16:31], v[4:7], v[108:111], v[16:31]
	s_waitcnt lgkmcnt(1)
	v_mfma_f32_32x32x16_bf16 v[16:31], v[0:3], v[112:115], v[16:31]
	ds_read_b128 v[0:3], v72 offset:96
	s_waitcnt lgkmcnt(0)
	v_mfma_f32_32x32x16_bf16 v[16:31], v[0:3], v[116:119], v[16:31]
	ds_read_b128 v[0:3], v72 offset:4608
	s_waitcnt lgkmcnt(0)
	v_mfma_f32_32x32x16_bf16 v[0:15], v[0:3], v[104:107], 0
	v_mfma_f32_32x32x16_bf16 v[0:15], v[32:35], v[108:111], v[0:15]
	ds_read_b128 v[32:35], v72 offset:4672
	s_waitcnt lgkmcnt(0)
	v_mfma_f32_32x32x16_bf16 v[0:15], v[32:35], v[112:115], v[0:15]
	ds_read_b128 v[32:35], v72 offset:4704
	s_waitcnt lgkmcnt(0)
	v_mfma_f32_32x32x16_bf16 v[0:15], v[32:35], v[116:119], v[0:15]
	v_mov_b32_e32 v32, 0
	v_mov_b32_e32 v33, v32
	v_mov_b32_e32 v34, v32
	v_mov_b32_e32 v35, v32
	v_mov_b32_e32 v36, v32
	v_mov_b32_e32 v37, v32
	v_mov_b32_e32 v38, v32
	v_mov_b32_e32 v39, v32
	v_mov_b32_e32 v40, v32
	v_mov_b32_e32 v41, v32
	v_mov_b32_e32 v42, v32
	v_mov_b32_e32 v43, v32
	v_mov_b32_e32 v44, v32
	v_mov_b32_e32 v45, v32
	v_mov_b32_e32 v46, v32
	v_mov_b32_e32 v47, v32
	s_cbranch_scc1 .LBB0_477
	ds_read_b128 v[32:35], v72 offset:9216
	ds_read_b128 v[48:51], v72 offset:9248
	s_waitcnt lgkmcnt(1)
	v_mfma_f32_32x32x16_bf16 v[32:47], v[32:35], v[104:107], 0
	s_waitcnt lgkmcnt(0)
	v_mfma_f32_32x32x16_bf16 v[32:47], v[48:51], v[108:111], v[32:47]
	ds_read_b128 v[48:51], v72 offset:9280
	s_waitcnt lgkmcnt(0)
	v_mfma_f32_32x32x16_bf16 v[32:47], v[48:51], v[112:115], v[32:47]
	ds_read_b128 v[48:51], v72 offset:9312
	s_waitcnt lgkmcnt(0)
	v_mfma_f32_32x32x16_bf16 v[32:47], v[48:51], v[116:119], v[32:47]

.LBB0_500:
	s_and_b64 vcc, exec, s[0:1]
	s_cbranch_vccz .LBB0_431
	v_lshlrev_b32_e32 v194, 2, v70
	s_nop 2
	v_lshrrev_b32_e32 v2, 2, v65
	v_or_b32_e32 v0, 0x80, v67
	v_mul_u32_u24_e32 v1, 0x90, v66
	v_and_or_b32 v2, v2, 3, v194
	v_lshlrev_b32_e32 v3, 1, v68
	v_lshlrev_b32_e32 v4, 3, v68
	v_and_b32_e32 v3, 32, v3
	v_and_b32_e32 v4, 24, v4
	v_sub_u32_e32 v167, v0, v194
	v_add3_u32 v168, 0, v1, v69
	v_mad_u32_u24 v0, v2, s21, 0
	v_and_b32_e32 v1, 64, v197
	v_add3_u32 v166, v0, v3, v4
	v_xor_b32_e32 v0, 32, v197
	v_add_u32_e32 v1, 64, v1
	v_cmp_lt_i32_e32 vcc, v0, v1
	v_cvt_f32_ubyte0_e32 v205, v167
	s_nop 0
	v_cndmask_b32_e32 v0, v197, v0, vcc
	v_lshlrev_b32_e32 v165, 2, v0
	ds_read_b128 v[0:3], v168
	ds_read_b128 v[4:7], v168 offset:32
	s_waitcnt lgkmcnt(1)
	v_mfma_f32_32x32x16_bf16 v[32:47], v[0:3], v[104:107], 0
	ds_read_b128 v[0:3], v168 offset:64
	ds_read_b128 v[48:51], v168 offset:9248
	s_waitcnt lgkmcnt(2)
	v_mfma_f32_32x32x16_bf16 v[32:47], v[4:7], v[108:111], v[32:47]
	s_waitcnt lgkmcnt(1)
	v_mfma_f32_32x32x16_bf16 v[32:47], v[0:3], v[112:115], v[32:47]
	ds_read_b128 v[0:3], v168 offset:96
	s_waitcnt lgkmcnt(0)
	v_mfma_f32_32x32x16_bf16 v[32:47], v[0:3], v[116:119], v[32:47]
	ds_read_b128 v[0:3], v168 offset:4608
	s_waitcnt lgkmcnt(0)
	v_mfma_f32_32x32x16_bf16 v[16:31], v[0:3], v[104:107], 0
	ds_read_b128 v[0:3], v168 offset:4640
	s_nop 7
	v_mov_b32_e32 v156, v32
	s_waitcnt lgkmcnt(0)
	v_mfma_f32_32x32x16_bf16 v[16:31], v[0:3], v[108:111], v[16:31]
	ds_read_b128 v[0:3], v168 offset:4672
	s_waitcnt lgkmcnt(0)
	v_mfma_f32_32x32x16_bf16 v[16:31], v[0:3], v[112:115], v[16:31]
	ds_read_b128 v[0:3], v168 offset:4704
	s_waitcnt lgkmcnt(0)
	v_mfma_f32_32x32x16_bf16 v[16:31], v[0:3], v[116:119], v[16:31]
	ds_read_b128 v[0:3], v168 offset:9216
	s_waitcnt lgkmcnt(0)
	v_mfma_f32_32x32x16_bf16 v[0:15], v[0:3], v[104:107], 0
	v_mfma_f32_32x32x16_bf16 v[0:15], v[48:51], v[108:111], v[0:15]
	ds_read_b128 v[48:51], v168 offset:9280
	s_waitcnt lgkmcnt(0)
	v_mfma_f32_32x32x16_bf16 v[0:15], v[48:51], v[112:115], v[0:15]
	ds_read_b128 v[48:51], v168 offset:9312
	s_waitcnt lgkmcnt(0)
	v_mfma_f32_32x32x16_bf16 v[0:15], v[48:51], v[116:119], v[0:15]
	v_mul_f32_e64 v48, v156, v204
	v_mul_f32_e64 v49, v157, v205
	v_mov_b32_e32 v156, v33
	v_sub_f32_e32 v32, v48, v49
	v_add_u32_e32 v48, -1, v167
	v_cvt_f32_u32_e32 v205, v48
	v_pk_mul_f32 v[48:49], v[156:157], v[204:205]
	s_nop 0
	v_sub_f32_e32 v33, v48, v49
	v_add_u32_e32 v48, -2, v167
	v_cvt_f32_u32_e32 v205, v48
	v_mov_b32_e32 v156, v34
	v_max3_f32 v50, v164, v32, v33
	v_pk_mul_f32 v[48:49], v[156:157], v[204:205]
	s_nop 0
	v_sub_f32_e32 v34, v48, v49
	v_add_u32_e32 v48, -3, v167
	v_cvt_f32_u32_e32 v205, v48
	v_mov_b32_e32 v156, v35
	v_pk_mul_f32 v[48:49], v[156:157], v[204:205]
	s_nop 0
	v_sub_f32_e32 v35, v48, v49
	v_add_u32_e32 v48, -8, v167
	v_cvt_f32_u32_e32 v205, v48
	v_mov_b32_e32 v156, v36
	v_max3_f32 v50, v50, v34, v35
	v_pk_mul_f32 v[48:49], v[156:157], v[204:205]
	s_nop 0
	v_sub_f32_e32 v36, v48, v49
	v_add_u32_e32 v48, -9, v167
	v_cvt_f32_u32_e32 v205, v48
	v_mov_b32_e32 v156, v37
	v_pk_mul_f32 v[48:49], v[156:157], v[204:205]
	s_nop 0
	v_sub_f32_e32 v37, v48, v49
	v_add_u32_e32 v48, -10, v167
	v_cvt_f32_u32_e32 v205, v48
	v_mov_b32_e32 v156, v38
	v_max3_f32 v50, v50, v36, v37
	v_pk_mul_f32 v[48:49], v[156:157], v[204:205]
	s_nop 0
	v_sub_f32_e32 v38, v48, v49
	v_add_u32_e32 v48, -11, v167
	v_cvt_f32_u32_e32 v205, v48
	v_mov_b32_e32 v156, v39
	v_pk_mul_f32 v[48:49], v[156:157], v[204:205]
	s_nop 0
	v_sub_f32_e32 v39, v48, v49
	v_add_u32_e32 v48, -16, v167
	v_cvt_f32_u32_e32 v205, v48
	v_mov_b32_e32 v156, v40
	v_max3_f32 v50, v50, v38, v39
	v_pk_mul_f32 v[48:49], v[156:157], v[204:205]
	s_nop 0
	v_sub_f32_e32 v40, v48, v49
	v_subrev_u32_e32 v48, 17, v167
	v_cvt_f32_u32_e32 v205, v48
	v_mov_b32_e32 v156, v41
	v_pk_mul_f32 v[48:49], v[156:157], v[204:205]
	s_nop 0
	v_sub_f32_e32 v41, v48, v49
	v_subrev_u32_e32 v48, 18, v167
	v_cvt_f32_u32_e32 v205, v48
	v_mov_b32_e32 v156, v42
	v_max3_f32 v50, v50, v40, v41
	v_pk_mul_f32 v[48:49], v[156:157], v[204:205]
	s_nop 0
	v_sub_f32_e32 v42, v48, v49
	v_subrev_u32_e32 v48, 19, v167
	v_cvt_f32_u32_e32 v205, v48
	v_mov_b32_e32 v156, v43
	v_pk_mul_f32 v[48:49], v[156:157], v[204:205]
	s_nop 0
	v_sub_f32_e32 v43, v48, v49
	v_subrev_u32_e32 v48, 24, v167
	v_cvt_f32_u32_e32 v205, v48
	v_mov_b32_e32 v156, v44
	v_max3_f32 v50, v50, v42, v43
	v_pk_mul_f32 v[48:49], v[156:157], v[204:205]
	s_nop 0
	v_sub_f32_e32 v44, v48, v49
	v_subrev_u32_e32 v48, 25, v167
	v_cvt_f32_u32_e32 v205, v48
	v_mov_b32_e32 v156, v45
	v_pk_mul_f32 v[48:49], v[156:157], v[204:205]
	s_nop 0
	v_sub_f32_e32 v45, v48, v49
	v_subrev_u32_e32 v48, 26, v167
	v_cvt_f32_u32_e32 v205, v48
	v_mov_b32_e32 v156, v46
	v_max3_f32 v50, v50, v44, v45
	v_pk_mul_f32 v[48:49], v[156:157], v[204:205]
	s_nop 0
	v_sub_f32_e32 v46, v48, v49
	v_subrev_u32_e32 v48, 27, v167
	v_cvt_f32_u32_e32 v205, v48
	v_mov_b32_e32 v156, v47
	v_pk_mul_f32 v[48:49], v[156:157], v[204:205]
	s_nop 0
	v_sub_f32_e32 v47, v48, v49
	v_subrev_u32_e32 v48, 32, v167
	v_cvt_f32_u32_e32 v205, v48
	v_mov_b32_e32 v156, v16
	v_max3_f32 v50, v50, v46, v47
	v_pk_mul_f32 v[48:49], v[156:157], v[204:205]
	s_nop 0
	v_sub_f32_e32 v16, v48, v49
	v_subrev_u32_e32 v48, 33, v167
	v_cvt_f32_u32_e32 v205, v48
	v_mov_b32_e32 v156, v17
	v_pk_mul_f32 v[48:49], v[156:157], v[204:205]
	s_nop 0
	v_sub_f32_e32 v17, v48, v49
	v_subrev_u32_e32 v48, 34, v167
	v_cvt_f32_u32_e32 v205, v48
	v_mov_b32_e32 v156, v18
	v_max3_f32 v50, v50, v16, v17
	v_pk_mul_f32 v[48:49], v[156:157], v[204:205]
	s_nop 0
	v_sub_f32_e32 v18, v48, v49
	v_subrev_u32_e32 v48, 35, v167
	v_cvt_f32_u32_e32 v205, v48
	v_mov_b32_e32 v156, v19
	v_pk_mul_f32 v[48:49], v[156:157], v[204:205]
	s_nop 0
	v_sub_f32_e32 v19, v48, v49
	v_subrev_u32_e32 v48, 40, v167
	v_cvt_f32_u32_e32 v205, v48
	v_mov_b32_e32 v156, v20
	v_max3_f32 v50, v50, v18, v19
	v_pk_mul_f32 v[48:49], v[156:157], v[204:205]
	s_nop 0
	v_sub_f32_e32 v20, v48, v49
	v_subrev_u32_e32 v48, 41, v167
	v_cvt_f32_u32_e32 v205, v48
	v_mov_b32_e32 v156, v21
	v_pk_mul_f32 v[48:49], v[156:157], v[204:205]
	s_nop 0
	v_sub_f32_e32 v21, v48, v49
	v_subrev_u32_e32 v48, 42, v167
	v_cvt_f32_u32_e32 v205, v48
	v_mov_b32_e32 v156, v22
	v_max3_f32 v50, v50, v20, v21
	v_pk_mul_f32 v[48:49], v[156:157], v[204:205]
	s_nop 0
	v_sub_f32_e32 v22, v48, v49
	v_subrev_u32_e32 v48, 43, v167
	v_cvt_f32_u32_e32 v205, v48
	v_mov_b32_e32 v156, v23
	v_pk_mul_f32 v[48:49], v[156:157], v[204:205]
	s_nop 0
	v_sub_f32_e32 v23, v48, v49
	v_subrev_u32_e32 v48, 48, v167
	v_cvt_f32_u32_e32 v205, v48
	v_mov_b32_e32 v156, v24
	v_max3_f32 v50, v50, v22, v23
	v_pk_mul_f32 v[48:49], v[156:157], v[204:205]
	s_nop 0
	v_sub_f32_e32 v24, v48, v49
	v_subrev_u32_e32 v48, 49, v167
	v_cvt_f32_u32_e32 v205, v48
	v_mov_b32_e32 v156, v25
	v_pk_mul_f32 v[48:49], v[156:157], v[204:205]
	s_nop 0
	v_sub_f32_e32 v25, v48, v49
	v_subrev_u32_e32 v48, 50, v167
	v_cvt_f32_u32_e32 v205, v48
	v_mov_b32_e32 v156, v26
	v_max3_f32 v50, v50, v24, v25
	v_pk_mul_f32 v[48:49], v[156:157], v[204:205]
	s_nop 0
	v_sub_f32_e32 v26, v48, v49
	v_subrev_u32_e32 v48, 51, v167
	v_cvt_f32_u32_e32 v205, v48
	v_mov_b32_e32 v156, v27
	v_pk_mul_f32 v[48:49], v[156:157], v[204:205]
	s_nop 0
	v_sub_f32_e32 v27, v48, v49
	v_subrev_u32_e32 v48, 56, v167
	v_cvt_f32_u32_e32 v205, v48
	v_mov_b32_e32 v156, v28
	v_subrev_u32_e32 v28, 57, v167
	v_max3_f32 v50, v50, v26, v27
	v_pk_mul_f32 v[48:49], v[156:157], v[204:205]
	v_cvt_f32_u32_e32 v205, v28
	v_mov_b32_e32 v156, v29
	v_sub_f32_e32 v48, v48, v49
	v_pk_mul_f32 v[28:29], v[156:157], v[204:205]
	s_nop 0
	v_sub_f32_e32 v49, v28, v29
	v_subrev_u32_e32 v28, 58, v167
	v_cvt_f32_u32_e32 v205, v28
	v_mov_b32_e32 v156, v30
	v_max3_f32 v50, v50, v48, v49
	v_pk_mul_f32 v[28:29], v[156:157], v[204:205]
	s_nop 0
	v_sub_f32_e32 v30, v28, v29
	v_subrev_u32_e32 v28, 59, v167
	v_cvt_f32_u32_e32 v205, v28
	v_mov_b32_e32 v156, v31
	v_pk_mul_f32 v[28:29], v[156:157], v[204:205]
	s_nop 0
	v_sub_f32_e32 v31, v28, v29
	v_subrev_u32_e32 v28, 64, v167
	v_cvt_f32_u32_e32 v205, v28
	v_mov_b32_e32 v156, v0
	v_add_u32_e32 v0, 0xffffffbf, v167
	v_max3_f32 v50, v50, v30, v31
	v_pk_mul_f32 v[28:29], v[156:157], v[204:205]
	v_cvt_f32_u32_e32 v205, v0
	v_mov_b32_e32 v156, v1
	v_sub_f32_e32 v28, v28, v29
	v_pk_mul_f32 v[0:1], v[156:157], v[204:205]
	s_nop 0
	v_sub_f32_e32 v29, v0, v1
	v_add_u32_e32 v0, 0xffffffbe, v167
	v_cvt_f32_u32_e32 v205, v0
	v_mov_b32_e32 v156, v2
	v_max3_f32 v50, v50, v28, v29
	v_pk_mul_f32 v[0:1], v[156:157], v[204:205]
	s_nop 0
	v_sub_f32_e32 v2, v0, v1
	v_add_u32_e32 v0, 0xffffffbd, v167
	v_cvt_f32_u32_e32 v205, v0
	v_mov_b32_e32 v156, v3
	v_pk_mul_f32 v[0:1], v[156:157], v[204:205]
	s_nop 0
	v_sub_f32_e32 v3, v0, v1
	v_add_u32_e32 v0, 0xffffffb8, v167
	v_cvt_f32_u32_e32 v205, v0
	v_mov_b32_e32 v156, v4
	v_max3_f32 v50, v50, v2, v3
	v_pk_mul_f32 v[0:1], v[156:157], v[204:205]
	s_nop 0
	v_sub_f32_e32 v4, v0, v1
	v_add_u32_e32 v0, 0xffffffb7, v167
	v_cvt_f32_u32_e32 v205, v0
	v_mov_b32_e32 v156, v5
	v_pk_mul_f32 v[0:1], v[156:157], v[204:205]
	s_nop 0
	v_sub_f32_e32 v5, v0, v1
	v_add_u32_e32 v0, 0xffffffb6, v167
	v_cvt_f32_u32_e32 v205, v0
	v_mov_b32_e32 v156, v6
	v_max3_f32 v50, v50, v4, v5
	v_pk_mul_f32 v[0:1], v[156:157], v[204:205]
	s_nop 0
	v_sub_f32_e32 v6, v0, v1
	v_add_u32_e32 v0, 0xffffffb5, v167
	v_cvt_f32_u32_e32 v205, v0
	v_mov_b32_e32 v156, v7
	v_pk_mul_f32 v[0:1], v[156:157], v[204:205]
	s_nop 0
	v_sub_f32_e32 v7, v0, v1
	v_add_u32_e32 v0, 0xffffffb0, v167
	v_cvt_f32_u32_e32 v205, v0
	v_mov_b32_e32 v156, v8
	v_max3_f32 v50, v50, v6, v7
	v_pk_mul_f32 v[0:1], v[156:157], v[204:205]
	s_nop 0
	v_sub_f32_e32 v8, v0, v1
	v_add_u32_e32 v0, 0xffffffaf, v167
	v_cvt_f32_u32_e32 v205, v0
	v_mov_b32_e32 v156, v9
	v_pk_mul_f32 v[0:1], v[156:157], v[204:205]
	s_nop 0
	v_sub_f32_e32 v9, v0, v1
	v_add_u32_e32 v0, 0xffffffae, v167
	v_cvt_f32_u32_e32 v205, v0
	v_mov_b32_e32 v156, v10
	v_max3_f32 v50, v50, v8, v9
	v_pk_mul_f32 v[0:1], v[156:157], v[204:205]
	s_nop 0
	v_sub_f32_e32 v10, v0, v1
	v_add_u32_e32 v0, 0xffffffad, v167
	v_cvt_f32_u32_e32 v205, v0
	v_mov_b32_e32 v156, v11
	v_pk_mul_f32 v[0:1], v[156:157], v[204:205]
	s_nop 0
	v_sub_f32_e32 v11, v0, v1
	v_add_u32_e32 v0, 0xffffffa8, v167
	v_cvt_f32_u32_e32 v205, v0
	v_mov_b32_e32 v156, v12
	v_max3_f32 v50, v50, v10, v11
	v_pk_mul_f32 v[0:1], v[156:157], v[204:205]
	s_nop 0
	v_sub_f32_e32 v12, v0, v1
	v_add_u32_e32 v0, 0xffffffa7, v167
	v_cvt_f32_u32_e32 v205, v0
	v_mov_b32_e32 v156, v13
	v_pk_mul_f32 v[0:1], v[156:157], v[204:205]
	s_nop 0
	v_sub_f32_e32 v13, v0, v1
	v_add_u32_e32 v0, 0xffffffa6, v167
	v_cvt_f32_u32_e32 v205, v0
	v_mov_b32_e32 v156, v14
	v_max3_f32 v50, v50, v12, v13
	v_pk_mul_f32 v[0:1], v[156:157], v[204:205]
	s_nop 0
	v_sub_f32_e32 v14, v0, v1
	v_add_u32_e32 v0, 0xffffffa5, v167
	v_cvt_f32_u32_e32 v205, v0
	v_mov_b32_e32 v156, v15
	v_pk_mul_f32 v[0:1], v[156:157], v[204:205]
	s_nop 0
	v_sub_f32_e32 v0, v0, v1
	v_max3_f32 v1, v50, v14, v0
	ds_bpermute_b32 v15, v165, v1
	v_add_u32_e32 v156, 0xffffffa0, v167
	v_cvt_f32_u32_e32 v205, v156
	s_waitcnt lgkmcnt(0)
	v_max_f32_e32 v15, v15, v15
	v_max_f32_e32 v169, v1, v15
	v_sub_f32_e32 v1, v32, v169
	v_exp_f32_e32 v170, v1
	v_sub_f32_e32 v1, v33, v169
	v_exp_f32_e32 v171, v1
	v_sub_f32_e32 v1, v34, v169
	v_exp_f32_e32 v172, v1
	v_sub_f32_e32 v1, v35, v169
	v_exp_f32_e32 v173, v1
	v_sub_f32_e32 v1, v36, v169
	v_exp_f32_e32 v174, v1
	v_sub_f32_e32 v1, v37, v169
	v_exp_f32_e32 v175, v1
	v_sub_f32_e32 v1, v38, v169
	v_exp_f32_e32 v176, v1
	v_sub_f32_e32 v1, v39, v169
	v_exp_f32_e32 v177, v1
	v_sub_f32_e32 v1, v40, v169
	v_exp_f32_e32 v178, v1
	v_sub_f32_e32 v1, v41, v169
	v_exp_f32_e32 v179, v1
	v_sub_f32_e32 v1, v42, v169
	v_exp_f32_e32 v180, v1
	v_sub_f32_e32 v1, v43, v169
	v_exp_f32_e32 v181, v1
	v_sub_f32_e32 v1, v44, v169
	v_exp_f32_e32 v182, v1
	v_sub_f32_e32 v1, v45, v169
	v_exp_f32_e32 v183, v1
	v_sub_f32_e32 v1, v46, v169
	v_exp_f32_e32 v184, v1
	v_sub_f32_e32 v1, v47, v169
	v_exp_f32_e32 v185, v1
	v_sub_f32_e32 v1, v16, v169
	v_exp_f32_e32 v186, v1
	v_sub_f32_e32 v1, v17, v169
	v_exp_f32_e32 v187, v1
	v_sub_f32_e32 v1, v18, v169
	v_exp_f32_e32 v188, v1
	v_sub_f32_e32 v1, v19, v169
	v_exp_f32_e32 v189, v1
	v_sub_f32_e32 v1, v20, v169
	v_exp_f32_e32 v190, v1
	v_sub_f32_e32 v1, v21, v169
	v_exp_f32_e32 v191, v1
	v_sub_f32_e32 v1, v22, v169
	v_exp_f32_e32 v202, v1
	v_sub_f32_e32 v1, v23, v169
	v_exp_f32_e32 v218, v1
	v_sub_f32_e32 v1, v24, v169
	v_exp_f32_e32 v219, v1
	v_sub_f32_e32 v1, v25, v169
	v_exp_f32_e32 v220, v1
	v_sub_f32_e32 v1, v26, v169
	v_exp_f32_e32 v221, v1
	v_sub_f32_e32 v1, v27, v169
	v_exp_f32_e32 v222, v1
	v_sub_f32_e32 v1, v48, v169
	v_exp_f32_e32 v223, v1
	v_sub_f32_e32 v1, v49, v169
	v_exp_f32_e32 v224, v1
	v_sub_f32_e32 v1, v30, v169
	v_exp_f32_e32 v225, v1
	v_sub_f32_e32 v1, v31, v169
	v_exp_f32_e32 v226, v1
	v_sub_f32_e32 v1, v28, v169
	v_exp_f32_e32 v227, v1
	v_sub_f32_e32 v1, v29, v169
	v_exp_f32_e32 v228, v1
	v_sub_f32_e32 v1, v2, v169
	v_exp_f32_e32 v229, v1
	v_sub_f32_e32 v1, v3, v169
	v_exp_f32_e32 v230, v1
	v_sub_f32_e32 v1, v4, v169
	v_exp_f32_e32 v231, v1
	v_sub_f32_e32 v1, v5, v169
	v_exp_f32_e32 v232, v1
	v_sub_f32_e32 v1, v6, v169
	v_exp_f32_e32 v233, v1
	v_sub_f32_e32 v1, v7, v169
	v_exp_f32_e32 v234, v1
	v_sub_f32_e32 v1, v8, v169
	v_exp_f32_e32 v235, v1
	v_sub_f32_e32 v1, v9, v169
	v_exp_f32_e32 v236, v1
	v_sub_f32_e32 v1, v10, v169
	v_exp_f32_e32 v237, v1
	v_sub_f32_e32 v1, v11, v169
	v_exp_f32_e32 v238, v1
	v_sub_f32_e32 v1, v12, v169
	v_exp_f32_e32 v239, v1
	v_sub_f32_e32 v1, v13, v169
	v_exp_f32_e32 v246, v1
	v_sub_f32_e32 v1, v14, v169
	v_sub_f32_e32 v0, v0, v169
	v_exp_f32_e32 v247, v1
	v_exp_f32_e32 v248, v0
	ds_read_b64_tr_b16 v[0:1], v166 offset:27648
	ds_read_b64_tr_b16 v[2:3], v166 offset:29184
	v_cvt_pk_bf16_f32 v16, v170, v171
	v_cvt_pk_bf16_f32 v17, v172, v173
	v_cvt_pk_bf16_f32 v18, v174, v175
	v_cvt_pk_bf16_f32 v19, v176, v177
	ds_read_b64_tr_b16 v[20:21], v166 offset:27712
	ds_read_b64_tr_b16 v[22:23], v166 offset:29248
	s_waitcnt lgkmcnt(2)
	v_mfma_f32_32x32x16_bf16 v[0:15], v[0:3], v[16:19], 0
	ds_read_b64_tr_b16 v[36:37], v166 offset:30720
	ds_read_b64_tr_b16 v[38:39], v166 offset:32256
	v_cvt_pk_bf16_f32 v32, v178, v179
	v_cvt_pk_bf16_f32 v33, v180, v181
	v_cvt_pk_bf16_f32 v34, v182, v183
	v_cvt_pk_bf16_f32 v35, v184, v185
	s_waitcnt lgkmcnt(2)
	v_mfma_f32_32x32x16_bf16 v[16:31], v[20:23], v[16:19], 0
	s_waitcnt lgkmcnt(0)
	v_mfma_f32_32x32x16_bf16 v[0:15], v[36:39], v[32:35], v[0:15]
	ds_read_b64_tr_b16 v[36:37], v166 offset:30784
	ds_read_b64_tr_b16 v[38:39], v166 offset:32320
	s_waitcnt lgkmcnt(0)
	v_mfma_f32_32x32x16_bf16 v[16:31], v[36:39], v[32:35], v[16:31]
	ds_read_b64_tr_b16 v[36:37], v166 offset:33792
	ds_read_b64_tr_b16 v[38:39], v166 offset:35328
	v_cvt_pk_bf16_f32 v32, v186, v187
	v_cvt_pk_bf16_f32 v33, v188, v189
	v_cvt_pk_bf16_f32 v34, v190, v191
	v_cvt_pk_bf16_f32 v35, v202, v218
	s_waitcnt lgkmcnt(0)
	s_nop 0
	v_mfma_f32_32x32x16_bf16 v[0:15], v[36:39], v[32:35], v[0:15]
	ds_read_b64_tr_b16 v[36:37], v166 offset:33856
	ds_read_b64_tr_b16 v[38:39], v166 offset:35392
	s_waitcnt lgkmcnt(0)
	v_mfma_f32_32x32x16_bf16 v[16:31], v[36:39], v[32:35], v[16:31]
	ds_read_b64_tr_b16 v[36:37], v166 offset:36864
	ds_read_b64_tr_b16 v[38:39], v166 offset:38400
	v_cvt_pk_bf16_f32 v32, v219, v220
	v_cvt_pk_bf16_f32 v33, v221, v222
	v_cvt_pk_bf16_f32 v34, v223, v224
	v_cvt_pk_bf16_f32 v35, v225, v226
	s_waitcnt lgkmcnt(0)
	s_nop 0
	v_mfma_f32_32x32x16_bf16 v[0:15], v[36:39], v[32:35], v[0:15]
	ds_read_b64_tr_b16 v[36:37], v166 offset:36928
	ds_read_b64_tr_b16 v[38:39], v166 offset:38464
	s_waitcnt lgkmcnt(0)
	v_mfma_f32_32x32x16_bf16 v[16:31], v[36:39], v[32:35], v[16:31]
	ds_read_b64_tr_b16 v[36:37], v166 offset:39936
	ds_read_b64_tr_b16 v[38:39], v166 offset:41472
	v_cvt_pk_bf16_f32 v32, v227, v228
	v_cvt_pk_bf16_f32 v33, v229, v230
	v_cvt_pk_bf16_f32 v34, v231, v232
	v_cvt_pk_bf16_f32 v35, v233, v234
	s_waitcnt lgkmcnt(0)
	s_nop 0
	v_mfma_f32_32x32x16_bf16 v[0:15], v[36:39], v[32:35], v[0:15]
	ds_read_b64_tr_b16 v[36:37], v166 offset:40000
	ds_read_b64_tr_b16 v[38:39], v166 offset:41536
	s_waitcnt lgkmcnt(0)
	v_mfma_f32_32x32x16_bf16 v[16:31], v[36:39], v[32:35], v[16:31]
	ds_read_b64_tr_b16 v[36:37], v166 offset:43008
	ds_read_b64_tr_b16 v[38:39], v166 offset:44544
	v_cvt_pk_bf16_f32 v32, v235, v236
	v_cvt_pk_bf16_f32 v33, v237, v238
	v_cvt_pk_bf16_f32 v34, v239, v246
	v_cvt_pk_bf16_f32 v35, v247, v248
	s_waitcnt lgkmcnt(0)
	s_nop 0
	v_mfma_f32_32x32x16_bf16 v[0:15], v[36:39], v[32:35], v[0:15]
	ds_read_b64_tr_b16 v[36:37], v166 offset:43072
	ds_read_b64_tr_b16 v[38:39], v166 offset:44608
	ds_read_b128 v[198:201], v168 offset:23072
	s_waitcnt lgkmcnt(1)
	v_mfma_f32_32x32x16_bf16 v[16:31], v[36:39], v[32:35], v[16:31]
	ds_read_b128 v[32:35], v168 offset:13824
	s_waitcnt lgkmcnt(0)
	v_mfma_f32_32x32x16_bf16 v[64:79], v[32:35], v[104:107], 0
	ds_read_b128 v[32:35], v168 offset:13856
	s_waitcnt lgkmcnt(0)
	v_mfma_f32_32x32x16_bf16 v[64:79], v[32:35], v[108:111], v[64:79]
	ds_read_b128 v[32:35], v168 offset:13888
	s_waitcnt lgkmcnt(0)
	v_mfma_f32_32x32x16_bf16 v[64:79], v[32:35], v[112:115], v[64:79]
	ds_read_b128 v[32:35], v168 offset:13920
	s_waitcnt lgkmcnt(0)
	v_mfma_f32_32x32x16_bf16 v[64:79], v[32:35], v[116:119], v[64:79]
	ds_read_b128 v[32:35], v168 offset:18432
	s_waitcnt lgkmcnt(0)
	v_mfma_f32_32x32x16_bf16 v[48:63], v[32:35], v[104:107], 0
	ds_read_b128 v[32:35], v168 offset:18464
	s_nop 7
	v_mov_b32_e32 v156, v64
	s_waitcnt lgkmcnt(0)
	v_mfma_f32_32x32x16_bf16 v[48:63], v[32:35], v[108:111], v[48:63]
	ds_read_b128 v[32:35], v168 offset:18496
	s_waitcnt lgkmcnt(0)
	v_mfma_f32_32x32x16_bf16 v[48:63], v[32:35], v[112:115], v[48:63]
	ds_read_b128 v[32:35], v168 offset:18528
	s_waitcnt lgkmcnt(0)
	v_mfma_f32_32x32x16_bf16 v[48:63], v[32:35], v[116:119], v[48:63]
	ds_read_b128 v[32:35], v168 offset:23040
	s_waitcnt lgkmcnt(0)
	v_mfma_f32_32x32x16_bf16 v[32:47], v[32:35], v[104:107], 0
	v_mfma_f32_32x32x16_bf16 v[32:47], v[198:201], v[108:111], v[32:47]
	ds_read_b128 v[198:201], v168 offset:23104
	s_waitcnt lgkmcnt(0)
	v_mfma_f32_32x32x16_bf16 v[32:47], v[198:201], v[112:115], v[32:47]
	ds_read_b128 v[198:201], v168 offset:23136
	s_waitcnt lgkmcnt(0)
	v_mfma_f32_32x32x16_bf16 v[32:47], v[198:201], v[116:119], v[32:47]
	v_mul_f32_e64 v198, v156, v204
	v_mul_f32_e64 v199, v157, v205
	v_add_u32_e32 v156, 0xffffff9f, v167
	v_cvt_f32_u32_e32 v205, v156
	v_mov_b32_e32 v156, v65
	v_sub_f32_e32 v64, v198, v199
	v_pk_mul_f32 v[198:199], v[156:157], v[204:205]
	v_add_u32_e32 v156, 0xffffff9e, v167
	v_cvt_f32_u32_e32 v205, v156
	v_mov_b32_e32 v156, v66
	v_sub_f32_e32 v65, v198, v199
	v_max3_f32 v168, v169, v64, v65
	v_pk_mul_f32 v[198:199], v[156:157], v[204:205]
	v_add_u32_e32 v156, 0xffffff9d, v167
	v_cvt_f32_u32_e32 v205, v156
	v_mov_b32_e32 v156, v67
	v_sub_f32_e32 v66, v198, v199
	v_pk_mul_f32 v[198:199], v[156:157], v[204:205]
	v_add_u32_e32 v156, 0xffffff98, v167
	v_cvt_f32_u32_e32 v205, v156
	v_mov_b32_e32 v156, v68
	v_sub_f32_e32 v67, v198, v199
	v_max3_f32 v168, v168, v66, v67
	v_pk_mul_f32 v[198:199], v[156:157], v[204:205]
	v_add_u32_e32 v156, 0xffffff97, v167
	v_cvt_f32_u32_e32 v205, v156
	v_mov_b32_e32 v156, v69
	v_sub_f32_e32 v68, v198, v199
	v_pk_mul_f32 v[198:199], v[156:157], v[204:205]
	v_add_u32_e32 v156, 0xffffff96, v167
	v_cvt_f32_u32_e32 v205, v156
	v_mov_b32_e32 v156, v70
	v_sub_f32_e32 v69, v198, v199
	v_max3_f32 v168, v168, v68, v69
	v_pk_mul_f32 v[198:199], v[156:157], v[204:205]
	v_add_u32_e32 v156, 0xffffff95, v167
	v_cvt_f32_u32_e32 v205, v156
	v_mov_b32_e32 v156, v71
	v_sub_f32_e32 v70, v198, v199
	v_pk_mul_f32 v[198:199], v[156:157], v[204:205]
	v_add_u32_e32 v156, 0xffffff90, v167
	v_cvt_f32_u32_e32 v205, v156
	v_mov_b32_e32 v156, v72
	v_add_u32_e32 v72, 0xffffff8f, v167
	v_sub_f32_e32 v71, v198, v199
	v_pk_mul_f32 v[198:199], v[156:157], v[204:205]
	v_cvt_f32_u32_e32 v205, v72
	v_mov_b32_e32 v156, v73
	v_max3_f32 v192, v168, v70, v71
	v_sub_f32_e32 v168, v198, v199
	v_pk_mul_f32 v[72:73], v[156:157], v[204:205]
	v_add_u32_e32 v156, 0xffffff8e, v167
	v_cvt_f32_u32_e32 v205, v156
	v_mov_b32_e32 v156, v74
	v_sub_f32_e32 v73, v72, v73
	v_max3_f32 v72, v192, v168, v73
	v_pk_mul_f32 v[198:199], v[156:157], v[204:205]
	v_add_u32_e32 v156, 0xffffff8d, v167
	v_cvt_f32_u32_e32 v205, v156
	v_mov_b32_e32 v156, v75
	v_sub_f32_e32 v74, v198, v199
	v_pk_mul_f32 v[198:199], v[156:157], v[204:205]
	v_add_u32_e32 v156, 0xffffff88, v167
	v_cvt_f32_u32_e32 v205, v156
	v_mov_b32_e32 v156, v76
	v_sub_f32_e32 v75, v198, v199
	v_max3_f32 v72, v72, v74, v75
	v_pk_mul_f32 v[198:199], v[156:157], v[204:205]
	v_add_u32_e32 v156, 0xffffff87, v167
	v_cvt_f32_u32_e32 v205, v156
	v_mov_b32_e32 v156, v77
	v_sub_f32_e32 v76, v198, v199
	v_pk_mul_f32 v[198:199], v[156:157], v[204:205]
	v_add_u32_e32 v156, 0xffffff86, v167
	v_cvt_f32_u32_e32 v205, v156
	v_mov_b32_e32 v156, v78
	v_add_u32_e32 v78, 0xffffff85, v167
	v_sub_f32_e32 v77, v198, v199
	v_pk_mul_f32 v[198:199], v[156:157], v[204:205]
	v_cvt_f32_u32_e32 v205, v78
	v_mov_b32_e32 v156, v79
	v_sub_f32_e32 v249, v198, v199
	v_max3_f32 v72, v72, v76, v77
	v_pk_mul_f32 v[78:79], v[156:157], v[204:205]
	v_mov_b32_e32 v156, v48
	v_sub_f32_e32 v78, v78, v79
	v_add_u32_e32 v79, 0xffffff80, v167
	v_cvt_f32_i32_e32 v79, v79
	v_max3_f32 v72, v72, v249, v78
	v_and_b32_e32 v205, 0x7fffffff, v79
	v_add_u32_e32 v79, 0xffffff7f, v167
	v_cvt_f32_i32_e32 v79, v79
	v_pk_mul_f32 v[198:199], v[156:157], v[204:205]
	v_mov_b32_e32 v156, v49
	v_sub_f32_e32 v48, v198, v199
	v_and_b32_e32 v205, 0x7fffffff, v79
	v_add_u32_e32 v79, 0xffffff7e, v167
	v_cvt_f32_i32_e32 v79, v79
	v_pk_mul_f32 v[198:199], v[156:157], v[204:205]
	v_mov_b32_e32 v156, v50
	v_sub_f32_e32 v49, v198, v199
	v_and_b32_e32 v205, 0x7fffffff, v79
	v_add_u32_e32 v79, 0xffffff7d, v167
	v_cvt_f32_i32_e32 v79, v79
	v_pk_mul_f32 v[198:199], v[156:157], v[204:205]
	v_mov_b32_e32 v156, v51
	v_sub_f32_e32 v50, v198, v199
	v_and_b32_e32 v205, 0x7fffffff, v79
	v_add_u32_e32 v79, 0xffffff78, v167
	v_cvt_f32_i32_e32 v79, v79
	v_pk_mul_f32 v[198:199], v[156:157], v[204:205]
	v_mov_b32_e32 v156, v52
	v_sub_f32_e32 v51, v198, v199
	v_and_b32_e32 v205, 0x7fffffff, v79
	v_add_u32_e32 v79, 0xffffff77, v167
	v_cvt_f32_i32_e32 v79, v79
	v_pk_mul_f32 v[198:199], v[156:157], v[204:205]
	v_mov_b32_e32 v156, v53
	v_sub_f32_e32 v52, v198, v199
	v_and_b32_e32 v205, 0x7fffffff, v79
	v_add_u32_e32 v79, 0xffffff76, v167
	v_cvt_f32_i32_e32 v79, v79
	v_pk_mul_f32 v[198:199], v[156:157], v[204:205]
	v_mov_b32_e32 v156, v54
	v_sub_f32_e32 v53, v198, v199
	v_and_b32_e32 v205, 0x7fffffff, v79
	v_add_u32_e32 v79, 0xffffff75, v167
	v_cvt_f32_i32_e32 v79, v79
	v_pk_mul_f32 v[198:199], v[156:157], v[204:205]
	v_mov_b32_e32 v156, v55
	v_sub_f32_e32 v54, v198, v199
	v_and_b32_e32 v205, 0x7fffffff, v79
	v_add_u32_e32 v79, 0xffffff70, v167
	v_cvt_f32_i32_e32 v79, v79
	v_pk_mul_f32 v[198:199], v[156:157], v[204:205]
	v_mov_b32_e32 v156, v56
	v_sub_f32_e32 v55, v198, v199
	v_and_b32_e32 v205, 0x7fffffff, v79
	v_add_u32_e32 v79, 0xffffff6f, v167
	v_cvt_f32_i32_e32 v79, v79
	v_pk_mul_f32 v[198:199], v[156:157], v[204:205]
	v_mov_b32_e32 v156, v57
	v_sub_f32_e32 v56, v198, v199
	v_and_b32_e32 v205, 0x7fffffff, v79
	v_add_u32_e32 v79, 0xffffff6e, v167
	v_cvt_f32_i32_e32 v79, v79
	v_pk_mul_f32 v[198:199], v[156:157], v[204:205]
	v_mov_b32_e32 v156, v58
	v_sub_f32_e32 v57, v198, v199
	v_and_b32_e32 v205, 0x7fffffff, v79
	v_add_u32_e32 v79, 0xffffff6d, v167
	v_cvt_f32_i32_e32 v79, v79
	v_pk_mul_f32 v[198:199], v[156:157], v[204:205]
	v_mov_b32_e32 v156, v59
	v_sub_f32_e32 v58, v198, v199
	v_and_b32_e32 v205, 0x7fffffff, v79
	v_add_u32_e32 v79, 0xffffff68, v167
	v_cvt_f32_i32_e32 v79, v79
	v_pk_mul_f32 v[198:199], v[156:157], v[204:205]
	v_mov_b32_e32 v156, v60
	v_sub_f32_e32 v59, v198, v199
	v_and_b32_e32 v205, 0x7fffffff, v79
	v_add_u32_e32 v79, 0xffffff67, v167
	v_cvt_f32_i32_e32 v79, v79
	v_pk_mul_f32 v[198:199], v[156:157], v[204:205]
	v_mov_b32_e32 v156, v61
	v_sub_f32_e32 v60, v198, v199
	v_and_b32_e32 v205, 0x7fffffff, v79
	v_add_u32_e32 v79, 0xffffff66, v167
	v_cvt_f32_i32_e32 v79, v79
	v_pk_mul_f32 v[198:199], v[156:157], v[204:205]
	v_mov_b32_e32 v156, v62
	v_sub_f32_e32 v61, v198, v199
	v_and_b32_e32 v205, 0x7fffffff, v79
	v_add_u32_e32 v79, 0xffffff65, v167
	v_cvt_f32_i32_e32 v79, v79
	v_pk_mul_f32 v[198:199], v[156:157], v[204:205]
	v_mov_b32_e32 v156, v63
	v_sub_f32_e32 v62, v198, v199
	v_and_b32_e32 v205, 0x7fffffff, v79
	v_add_u32_e32 v79, 0xffffff60, v167
	v_cvt_f32_i32_e32 v79, v79
	v_pk_mul_f32 v[198:199], v[156:157], v[204:205]
	v_mov_b32_e32 v156, v32
	v_sub_f32_e32 v63, v198, v199
	v_and_b32_e32 v205, 0x7fffffff, v79
	v_add_u32_e32 v79, 0xffffff5f, v167
	v_cvt_f32_i32_e32 v79, v79
	v_pk_mul_f32 v[198:199], v[156:157], v[204:205]
	v_mov_b32_e32 v156, v33
	v_sub_f32_e32 v32, v198, v199
	v_and_b32_e32 v205, 0x7fffffff, v79
	v_add_u32_e32 v79, 0xffffff5e, v167
	v_cvt_f32_i32_e32 v79, v79
	v_pk_mul_f32 v[198:199], v[156:157], v[204:205]
	v_mov_b32_e32 v156, v34
	v_sub_f32_e32 v33, v198, v199
	v_and_b32_e32 v205, 0x7fffffff, v79
	v_add_u32_e32 v79, 0xffffff5d, v167
	v_cvt_f32_i32_e32 v79, v79
	v_pk_mul_f32 v[198:199], v[156:157], v[204:205]
	v_mov_b32_e32 v156, v35
	v_sub_f32_e32 v34, v198, v199
	v_and_b32_e32 v205, 0x7fffffff, v79
	v_add_u32_e32 v79, 0xffffff58, v167
	v_cvt_f32_i32_e32 v79, v79
	v_pk_mul_f32 v[198:199], v[156:157], v[204:205]
	v_mov_b32_e32 v156, v36
	v_sub_f32_e32 v35, v198, v199
	v_and_b32_e32 v205, 0x7fffffff, v79
	v_add_u32_e32 v79, 0xffffff57, v167
	v_cvt_f32_i32_e32 v79, v79
	v_pk_mul_f32 v[198:199], v[156:157], v[204:205]
	v_max3_f32 v72, v72, v48, v49
	v_max3_f32 v72, v72, v50, v51
	v_and_b32_e32 v205, 0x7fffffff, v79
	v_add_u32_e32 v79, 0xffffff56, v167
	v_cvt_f32_i32_e32 v79, v79
	v_max3_f32 v72, v72, v52, v53
	v_mov_b32_e32 v156, v37
	v_max3_f32 v72, v72, v54, v55
	v_sub_f32_e32 v36, v198, v199
	v_pk_mul_f32 v[198:199], v[156:157], v[204:205]
	v_and_b32_e32 v205, 0x7fffffff, v79
	v_add_u32_e32 v79, 0xffffff55, v167
	v_max3_f32 v72, v72, v56, v57
	v_cvt_f32_i32_e32 v79, v79
	v_max3_f32 v72, v72, v58, v59
	v_max3_f32 v72, v72, v60, v61
	v_max3_f32 v72, v72, v62, v63
	v_mov_b32_e32 v156, v38
	v_max3_f32 v72, v72, v32, v33
	v_sub_f32_e32 v37, v198, v199
	v_pk_mul_f32 v[198:199], v[156:157], v[204:205]
	v_and_b32_e32 v205, 0x7fffffff, v79
	v_mov_b32_e32 v156, v39
	v_max3_f32 v72, v72, v34, v35
	v_sub_f32_e32 v38, v198, v199
	v_pk_mul_f32 v[198:199], v[156:157], v[204:205]
	v_max3_f32 v72, v72, v36, v37
	v_sub_f32_e32 v79, v198, v199
	v_max3_f32 v39, v72, v38, v79
	v_add_u32_e32 v72, 0xffffff50, v167
	v_cvt_f32_i32_e32 v72, v72
	v_mov_b32_e32 v156, v40
	v_add_u32_e32 v40, 0xffffff4f, v167
	v_cvt_f32_i32_e32 v40, v40
	v_and_b32_e32 v205, 0x7fffffff, v72
	v_pk_mul_f32 v[198:199], v[156:157], v[204:205]
	v_mov_b32_e32 v156, v41
	v_and_b32_e32 v205, 0x7fffffff, v40
	v_pk_mul_f32 v[40:41], v[156:157], v[204:205]
	v_mov_b32_e32 v156, v42
	v_sub_f32_e32 v251, v40, v41
	v_add_u32_e32 v40, 0xffffff4e, v167
	v_cvt_f32_i32_e32 v40, v40
	v_sub_f32_e32 v250, v198, v199
	v_max3_f32 v39, v39, v250, v251
	v_and_b32_e32 v205, 0x7fffffff, v40
	v_pk_mul_f32 v[40:41], v[156:157], v[204:205]
	v_mov_b32_e32 v156, v43
	v_sub_f32_e32 v252, v40, v41
	v_add_u32_e32 v40, 0xffffff4d, v167
	v_cvt_f32_i32_e32 v40, v40
	v_and_b32_e32 v205, 0x7fffffff, v40
	v_pk_mul_f32 v[40:41], v[156:157], v[204:205]
	v_mov_b32_e32 v156, v44
	v_sub_f32_e32 v192, v40, v41
	v_add_u32_e32 v40, 0xffffff48, v167
	v_cvt_f32_i32_e32 v40, v40
	v_max3_f32 v39, v39, v252, v192
	v_and_b32_e32 v205, 0x7fffffff, v40
	v_pk_mul_f32 v[40:41], v[156:157], v[204:205]
	v_mov_b32_e32 v156, v45
	v_sub_f32_e32 v240, v40, v41
	v_add_u32_e32 v40, 0xffffff47, v167
	v_cvt_f32_i32_e32 v40, v40
	v_and_b32_e32 v205, 0x7fffffff, v40
	v_pk_mul_f32 v[40:41], v[156:157], v[204:205]
	v_mov_b32_e32 v156, v46
	v_sub_f32_e32 v241, v40, v41
	v_add_u32_e32 v40, 0xffffff46, v167
	v_cvt_f32_i32_e32 v40, v40
	v_max3_f32 v39, v39, v240, v241
	v_and_b32_e32 v205, 0x7fffffff, v40
	v_pk_mul_f32 v[40:41], v[156:157], v[204:205]
	v_mov_b32_e32 v156, v47
	v_sub_f32_e32 v198, v40, v41
	v_add_u32_e32 v40, 0xffffff45, v167
	v_cvt_f32_i32_e32 v40, v40
	v_and_b32_e32 v205, 0x7fffffff, v40
	v_pk_mul_f32 v[40:41], v[156:157], v[204:205]
	s_nop 0
	v_sub_f32_e32 v156, v40, v41
	v_max3_f32 v39, v39, v198, v156
	ds_bpermute_b32 v40, v165, v39
	s_waitcnt lgkmcnt(0)
	v_max_f32_e32 v40, v40, v40
	v_max_f32_e32 v72, v39, v40
	v_add_f32_e32 v39, 0, v170
	v_add_f32_e32 v39, v171, v39
	v_add_f32_e32 v39, v172, v39
	v_add_f32_e32 v39, v173, v39
	v_add_f32_e32 v39, v174, v39
	v_add_f32_e32 v39, v175, v39
	v_add_f32_e32 v39, v176, v39
	v_add_f32_e32 v39, v177, v39
	v_add_f32_e32 v39, v178, v39
	v_add_f32_e32 v39, v179, v39
	v_add_f32_e32 v39, v180, v39
	v_add_f32_e32 v39, v181, v39
	v_add_f32_e32 v39, v182, v39
	v_add_f32_e32 v39, v183, v39
	v_add_f32_e32 v39, v184, v39
	v_add_f32_e32 v39, v185, v39
	v_add_f32_e32 v39, v186, v39
	v_add_f32_e32 v39, v187, v39
	v_add_f32_e32 v39, v188, v39
	v_add_f32_e32 v39, v189, v39
	v_add_f32_e32 v39, v190, v39
	v_add_f32_e32 v39, v191, v39
	v_add_f32_e32 v39, v202, v39
	v_add_f32_e32 v39, v218, v39
	v_add_f32_e32 v39, v219, v39
	v_add_f32_e32 v39, v220, v39
	v_add_f32_e32 v39, v221, v39
	v_add_f32_e32 v39, v222, v39
	v_add_f32_e32 v39, v223, v39
	v_add_f32_e32 v39, v224, v39
	v_add_f32_e32 v39, v225, v39
	v_add_f32_e32 v39, v226, v39
	v_add_f32_e32 v39, v227, v39
	v_add_f32_e32 v39, v228, v39
	v_add_f32_e32 v39, v229, v39
	v_add_f32_e32 v39, v230, v39
	v_add_f32_e32 v39, v231, v39
	v_add_f32_e32 v39, v232, v39
	v_add_f32_e32 v39, v233, v39
	v_sub_f32_e32 v40, v169, v72
	v_add_f32_e32 v39, v234, v39
	v_exp_f32_e32 v40, v40
	v_add_f32_e32 v39, v235, v39
	v_add_f32_e32 v39, v236, v39
	v_add_f32_e32 v39, v237, v39
	v_add_f32_e32 v39, v238, v39
	v_pk_mul_f32 v[30:31], v[30:31], v[40:41] op_sel_hi:[1,0]
	v_pk_mul_f32 v[28:29], v[28:29], v[40:41] op_sel_hi:[1,0]
	v_pk_mul_f32 v[26:27], v[26:27], v[40:41] op_sel_hi:[1,0]
	v_pk_mul_f32 v[24:25], v[24:25], v[40:41] op_sel_hi:[1,0]
	v_pk_mul_f32 v[22:23], v[22:23], v[40:41] op_sel_hi:[1,0]
	v_pk_mul_f32 v[20:21], v[20:21], v[40:41] op_sel_hi:[1,0]
	v_pk_mul_f32 v[18:19], v[18:19], v[40:41] op_sel_hi:[1,0]
	v_pk_mul_f32 v[16:17], v[16:17], v[40:41] op_sel_hi:[1,0]
	v_pk_mul_f32 v[14:15], v[14:15], v[40:41] op_sel_hi:[1,0]
	v_pk_mul_f32 v[12:13], v[12:13], v[40:41] op_sel_hi:[1,0]
	v_pk_mul_f32 v[10:11], v[10:11], v[40:41] op_sel_hi:[1,0]
	v_pk_mul_f32 v[8:9], v[8:9], v[40:41] op_sel_hi:[1,0]
	v_pk_mul_f32 v[6:7], v[6:7], v[40:41] op_sel_hi:[1,0]
	v_pk_mul_f32 v[4:5], v[4:5], v[40:41] op_sel_hi:[1,0]
	v_pk_mul_f32 v[2:3], v[2:3], v[40:41] op_sel_hi:[1,0]
	v_pk_mul_f32 v[0:1], v[0:1], v[40:41] op_sel_hi:[1,0]
	v_sub_f32_e32 v41, v64, v72
	v_add_f32_e32 v39, v239, v39
	v_exp_f32_e32 v64, v41
	v_add_f32_e32 v39, v246, v39
	v_add_f32_e32 v39, v247, v39
	v_add_f32_e32 v39, v248, v39
	v_fma_f32 v39, v39, v40, v64
	v_sub_f32_e32 v40, v65, v72
	v_exp_f32_e32 v65, v40
	v_sub_f32_e32 v40, v66, v72
	v_exp_f32_e32 v66, v40
	v_sub_f32_e32 v40, v67, v72
	v_exp_f32_e32 v67, v40
	v_sub_f32_e32 v40, v68, v72
	v_exp_f32_e32 v68, v40
	v_sub_f32_e32 v40, v69, v72
	v_exp_f32_e32 v69, v40
	v_sub_f32_e32 v40, v70, v72
	v_exp_f32_e32 v70, v40
	v_sub_f32_e32 v40, v71, v72
	v_exp_f32_e32 v71, v40
	v_sub_f32_e32 v40, v168, v72
	v_exp_f32_e32 v157, v40
	v_sub_f32_e32 v40, v73, v72
	v_exp_f32_e32 v73, v40
	v_sub_f32_e32 v40, v74, v72
	v_exp_f32_e32 v74, v40
	v_sub_f32_e32 v40, v75, v72
	v_exp_f32_e32 v75, v40
	v_sub_f32_e32 v40, v76, v72
	v_exp_f32_e32 v76, v40
	v_sub_f32_e32 v40, v77, v72
	v_exp_f32_e32 v77, v40
	v_sub_f32_e32 v40, v249, v72
	v_exp_f32_e32 v167, v40
	v_sub_f32_e32 v40, v78, v72
	v_exp_f32_e32 v78, v40
	v_sub_f32_e32 v40, v48, v72
	v_exp_f32_e32 v168, v40
	v_sub_f32_e32 v40, v49, v72
	v_exp_f32_e32 v49, v40
	v_sub_f32_e32 v40, v50, v72
	v_exp_f32_e32 v169, v40
	v_sub_f32_e32 v40, v51, v72
	v_exp_f32_e32 v170, v40
	v_sub_f32_e32 v40, v52, v72
	v_exp_f32_e32 v171, v40
	v_sub_f32_e32 v40, v53, v72
	v_exp_f32_e32 v172, v40
	v_sub_f32_e32 v40, v54, v72
	v_exp_f32_e32 v173, v40
	v_sub_f32_e32 v40, v55, v72
	v_exp_f32_e32 v174, v40
	v_sub_f32_e32 v40, v56, v72
	v_exp_f32_e32 v175, v40
	v_sub_f32_e32 v40, v57, v72
	ds_read_b64_tr_b16 v[54:55], v166 offset:46080
	ds_read_b64_tr_b16 v[56:57], v166 offset:47616
	v_cvt_pk_bf16_f32 v50, v64, v65
	v_cvt_pk_bf16_f32 v51, v66, v67
	v_cvt_pk_bf16_f32 v52, v68, v69
	v_cvt_pk_bf16_f32 v53, v70, v71
	v_add_f32_e32 v39, v65, v39
	v_add_f32_e32 v39, v66, v39
	s_waitcnt lgkmcnt(0)
	v_mfma_f32_32x32x16_bf16 v[0:15], v[54:57], v[50:53], v[0:15]
	ds_read_b64_tr_b16 v[54:55], v166 offset:46144
	ds_read_b64_tr_b16 v[56:57], v166 offset:47680
	v_add_f32_e32 v39, v67, v39
	v_add_f32_e32 v39, v68, v39
	v_add_f32_e32 v39, v69, v39
	v_add_f32_e32 v39, v70, v39
	v_add_f32_e32 v39, v71, v39
	v_add_f32_e32 v39, v157, v39
	s_waitcnt lgkmcnt(0)
	v_mfma_f32_32x32x16_bf16 v[16:31], v[54:57], v[50:53], v[16:31]
	ds_read_b64_tr_b16 v[54:55], v166 offset:49152
	ds_read_b64_tr_b16 v[56:57], v166 offset:50688
	v_cvt_pk_bf16_f32 v50, v157, v73
	v_cvt_pk_bf16_f32 v51, v74, v75
	v_cvt_pk_bf16_f32 v52, v76, v77
	v_cvt_pk_bf16_f32 v53, v167, v78
	v_add_f32_e32 v39, v73, v39
	v_exp_f32_e32 v176, v40
	s_waitcnt lgkmcnt(0)
	v_mfma_f32_32x32x16_bf16 v[0:15], v[54:57], v[50:53], v[0:15]
	ds_read_b64_tr_b16 v[54:55], v166 offset:49216
	ds_read_b64_tr_b16 v[56:57], v166 offset:50752
	v_sub_f32_e32 v40, v58, v72
	v_add_f32_e32 v39, v74, v39
	v_exp_f32_e32 v58, v40
	v_sub_f32_e32 v40, v59, v72
	v_add_f32_e32 v39, v75, v39
	v_exp_f32_e32 v59, v40
	s_waitcnt lgkmcnt(0)
	v_mfma_f32_32x32x16_bf16 v[16:31], v[54:57], v[50:53], v[16:31]
	ds_read_b64_tr_b16 v[54:55], v166 offset:52224
	ds_read_b64_tr_b16 v[56:57], v166 offset:53760
	v_cvt_pk_bf16_f32 v50, v168, v49
	v_cvt_pk_bf16_f32 v51, v169, v170
	v_cvt_pk_bf16_f32 v52, v171, v172
	v_cvt_pk_bf16_f32 v53, v173, v174
	v_sub_f32_e32 v40, v60, v72
	v_add_f32_e32 v39, v76, v39
	s_waitcnt lgkmcnt(0)
	v_mfma_f32_32x32x16_bf16 v[0:15], v[54:57], v[50:53], v[0:15]
	ds_read_b64_tr_b16 v[54:55], v166 offset:52288
	ds_read_b64_tr_b16 v[56:57], v166 offset:53824
	v_exp_f32_e32 v60, v40
	v_sub_f32_e32 v40, v61, v72
	v_add_f32_e32 v39, v77, v39
	v_exp_f32_e32 v61, v40
	v_sub_f32_e32 v40, v62, v72
	v_add_f32_e32 v39, v167, v39
	v_exp_f32_e32 v62, v40
	v_sub_f32_e32 v40, v63, v72
	v_add_f32_e32 v39, v78, v39
	v_exp_f32_e32 v63, v40
	s_waitcnt lgkmcnt(0)
	v_mfma_f32_32x32x16_bf16 v[16:31], v[54:57], v[50:53], v[16:31]
	ds_read_b64_tr_b16 v[54:55], v166 offset:55296
	ds_read_b64_tr_b16 v[56:57], v166 offset:56832
	v_add_f32_e32 v39, v168, v39
	v_add_f32_e32 v39, v49, v39
	v_add_f32_e32 v39, v169, v39
	v_add_f32_e32 v39, v170, v39
	v_cvt_pk_bf16_f32 v50, v175, v176
	v_cvt_pk_bf16_f32 v51, v58, v59
	v_cvt_pk_bf16_f32 v52, v60, v61
	v_cvt_pk_bf16_f32 v53, v62, v63
	v_add_f32_e32 v39, v171, v39
	v_add_f32_e32 v39, v172, v39
	s_waitcnt lgkmcnt(0)
	v_mfma_f32_32x32x16_bf16 v[0:15], v[54:57], v[50:53], v[0:15]
	ds_read_b64_tr_b16 v[54:55], v166 offset:55360
	ds_read_b64_tr_b16 v[56:57], v166 offset:56896
	v_add_f32_e32 v39, v173, v39
	v_add_f32_e32 v39, v174, v39
	v_add_f32_e32 v39, v175, v39
	v_sub_f32_e32 v32, v32, v72
	v_sub_f32_e32 v33, v33, v72
	v_sub_f32_e32 v34, v34, v72
	v_sub_f32_e32 v35, v35, v72
	v_sub_f32_e32 v36, v36, v72
	v_sub_f32_e32 v37, v37, v72
	v_sub_f32_e32 v38, v38, v72
	v_sub_f32_e32 v40, v79, v72
	v_add_f32_e32 v39, v176, v39
	v_exp_f32_e32 v32, v32
	v_exp_f32_e32 v33, v33
	v_exp_f32_e32 v34, v34
	v_exp_f32_e32 v35, v35
	v_exp_f32_e32 v36, v36
	v_exp_f32_e32 v37, v37
	v_exp_f32_e32 v38, v38
	v_exp_f32_e32 v40, v40
	s_waitcnt lgkmcnt(0)
	v_mfma_f32_32x32x16_bf16 v[16:31], v[54:57], v[50:53], v[16:31]
	ds_read_b64_tr_b16 v[54:55], v166 offset:58368
	ds_read_b64_tr_b16 v[56:57], v166 offset:59904
	v_add_f32_e32 v39, v58, v39
	v_add_f32_e32 v39, v59, v39
	v_add_f32_e32 v39, v60, v39
	v_add_f32_e32 v39, v61, v39
	v_cvt_pk_bf16_f32 v50, v32, v33
	v_cvt_pk_bf16_f32 v51, v34, v35
	v_cvt_pk_bf16_f32 v52, v36, v37
	v_cvt_pk_bf16_f32 v53, v38, v40
	v_add_f32_e32 v39, v62, v39
	v_add_f32_e32 v39, v63, v39
	s_waitcnt lgkmcnt(0)
	v_mfma_f32_32x32x16_bf16 v[0:15], v[54:57], v[50:53], v[0:15]
	ds_read_b64_tr_b16 v[54:55], v166 offset:58432
	ds_read_b64_tr_b16 v[56:57], v166 offset:59968
	v_add_f32_e32 v32, v32, v39
	v_add_f32_e32 v32, v33, v32
	v_sub_f32_e32 v41, v250, v72
	v_sub_f32_e32 v42, v251, v72
	v_sub_f32_e32 v43, v252, v72
	v_sub_f32_e32 v44, v192, v72
	v_sub_f32_e32 v45, v240, v72
	v_sub_f32_e32 v46, v241, v72
	v_sub_f32_e32 v47, v198, v72
	v_sub_f32_e32 v48, v156, v72
	v_add_f32_e32 v32, v34, v32
	v_exp_f32_e32 v41, v41
	v_exp_f32_e32 v42, v42
	v_exp_f32_e32 v43, v43
	v_exp_f32_e32 v44, v44
	v_exp_f32_e32 v45, v45
	v_exp_f32_e32 v46, v46
	v_exp_f32_e32 v47, v47
	v_exp_f32_e32 v48, v48
	s_waitcnt lgkmcnt(0)
	v_mfma_f32_32x32x16_bf16 v[16:31], v[54:57], v[50:53], v[16:31]
	ds_read_b64_tr_b16 v[54:55], v166 offset:61440
	ds_read_b64_tr_b16 v[56:57], v166 offset:62976
	v_add_f32_e32 v32, v35, v32
	v_add_f32_e32 v32, v36, v32
	v_add_f32_e32 v32, v37, v32
	v_add_f32_e32 v32, v38, v32
	v_cvt_pk_bf16_f32 v50, v41, v42
	v_cvt_pk_bf16_f32 v51, v43, v44
	v_cvt_pk_bf16_f32 v52, v45, v46
	v_cvt_pk_bf16_f32 v53, v47, v48
	v_add_f32_e32 v32, v40, v32
	v_add_f32_e32 v32, v41, v32
	s_waitcnt lgkmcnt(0)
	v_mfma_f32_32x32x16_bf16 v[0:15], v[54:57], v[50:53], v[0:15]
	ds_read_b64_tr_b16 v[54:55], v166 offset:61504
	ds_read_b64_tr_b16 v[56:57], v166 offset:63040
	v_add_f32_e32 v32, v42, v32
	v_add_f32_e32 v32, v43, v32
	v_add_f32_e32 v32, v44, v32
	v_add_f32_e32 v32, v45, v32
	v_add_f32_e32 v32, v46, v32
	v_add_f32_e32 v32, v47, v32
	s_waitcnt lgkmcnt(0)
	v_mfma_f32_32x32x16_bf16 v[16:31], v[54:57], v[50:53], v[16:31]
	v_add_f32_e32 v74, v48, v32
	ds_bpermute_b32 v32, v165, v74
	s_branch .LBB0_431

	.amdhsa_kernel _Z8fwd_mega4Args
		.amdhsa_group_segment_fixed_size 0
		.amdhsa_private_segment_fixed_size 0
		.amdhsa_kernarg_size 464
		.amdhsa_user_sgpr_count 2
		.amdhsa_user_sgpr_dispatch_ptr 0
		.amdhsa_user_sgpr_queue_ptr 0
		.amdhsa_user_sgpr_kernarg_segment_ptr 1
		.amdhsa_user_sgpr_dispatch_id 0
		.amdhsa_user_sgpr_kernarg_preload_length 0
		.amdhsa_user_sgpr_kernarg_preload_offset 0
		.amdhsa_user_sgpr_private_segment_size 0
		.amdhsa_uses_dynamic_stack 0
		.amdhsa_enable_private_segment 0
		.amdhsa_system_sgpr_workgroup_id_x 1
		.amdhsa_system_sgpr_workgroup_id_y 0
		.amdhsa_system_sgpr_workgroup_id_z 0
		.amdhsa_system_sgpr_workgroup_info 0
		.amdhsa_system_vgpr_workitem_id 2
		.amdhsa_next_free_vgpr 256
		.amdhsa_next_free_sgpr 102
		.amdhsa_accum_offset 256
		.amdhsa_reserve_vcc 1
		.amdhsa_float_round_mode_32 0
		.amdhsa_float_round_mode_16_64 0
		.amdhsa_float_denorm_mode_32 3
		.amdhsa_float_denorm_mode_16_64 3
		.amdhsa_dx10_clamp 1
		.amdhsa_ieee_mode 1
		.amdhsa_fp16_overflow 0
		.amdhsa_tg_split 0
		.amdhsa_exception_fp_ieee_invalid_op 0
		.amdhsa_exception_fp_denorm_src 0
		.amdhsa_exception_fp_ieee_div_zero 0
		.amdhsa_exception_fp_ieee_overflow 0
		.amdhsa_exception_fp_ieee_underflow 0
		.amdhsa_exception_fp_ieee_inexact 0
		.amdhsa_exception_int_div_zero 0
	.end_amdhsa_kernel

amdhsa.kernels:
  - .agpr_count:     0
    .args:
      - .offset:         0
        .size:           208
        .value_kind:     by_value
      - .offset:         208
        .size:           4
        .value_kind:     hidden_block_count_x
      - .offset:         212
        .size:           4
        .value_kind:     hidden_block_count_y
      - .offset:         216
        .size:           4
        .value_kind:     hidden_block_count_z
      - .offset:         220
        .size:           2
        .value_kind:     hidden_group_size_x
      - .offset:         222
        .size:           2
        .value_kind:     hidden_group_size_y
      - .offset:         224
        .size:           2
        .value_kind:     hidden_group_size_z
      - .offset:         226
        .size:           2
        .value_kind:     hidden_remainder_x
      - .offset:         228
        .size:           2
        .value_kind:     hidden_remainder_y
      - .offset:         230
        .size:           2
        .value_kind:     hidden_remainder_z
      - .offset:         248
        .size:           8
        .value_kind:     hidden_global_offset_x
      - .offset:         256
        .size:           8
        .value_kind:     hidden_global_offset_y
      - .offset:         264
        .size:           8
        .value_kind:     hidden_global_offset_z
      - .offset:         272
        .size:           2
        .value_kind:     hidden_grid_dims
      - .offset:         296
        .size:           8
        .value_kind:     hidden_multigrid_sync_arg
      - .offset:         328
        .size:           4
        .value_kind:     hidden_dynamic_lds_size
    .group_segment_fixed_size: 0
    .kernarg_segment_align: 8
    .kernarg_segment_size: 464
    .language:       OpenCL C
    .language_version:
      - 2
      - 0
    .max_flat_workgroup_size: 512
    .name:           _Z8fwd_mega4Args
    .private_segment_fixed_size: 0
    .sgpr_count:     108
    .sgpr_spill_count: 194
    .symbol:         _Z8fwd_mega4Args.kd
    .uniform_work_group_size: 1
    .uses_dynamic_stack: false
    .vgpr_count:     256
    .vgpr_spill_count: 0
    .wavefront_size: 64
